# out-proj (bf16 residual, rowscale) epilogue rewritten like the down one: loads 5 groups ahead, rs via 8 early ds_reads
# speedup vs baseline: 1.0268x; 1.0020x over previous
;     __device__ __forceinline__ void load_x(f32x4 (&x)[2][2], size_t off) const {
; #pragma unroll
;         for (int bj = 0; bj < 2; ++bj) {
;             if constexpr (XIN_F32) { x[bj][0] = *(const f32x4*)((const float*)xin + off + bj * HALF); x[bj][1] = *(const f32x4*)((const float*)xin + off + bj * HALF + 4); }
;             else { const u32x4 w = *(const u32x4*)((const bf16_t*)xin + off + bj * HALF);
;                 x[bj][0] = (f32x4){__builtin_bit_cast(float, w.x << 16), __builtin_bit_cast(float, w.x & 0xffff0000u), __builtin_bit_cast(float, w.y << 16), __builtin_bit_cast(float, w.y & 0xffff0000u)};
;                 x[bj][1] = (f32x4){__builtin_bit_cast(float, w.z << 16), __builtin_bit_cast(float, w.z & 0xffff0000u), __builtin_bit_cast(float, w.w << 16), __builtin_bit_cast(float, w.w & 0xffff0000u)}; } }
;     }
;     __device__ __forceinline__ void operator()(const f32x4 (&acc)[2][2][4][2], const Unit& u, int wr, int wc, int fr, int fq) const {
;         const int row0 = u.pm * BM + wr * 64 + fr; const int col0 = u.pn * BM + wc * 32 + 8 * fq;
;         const int b = (u.pm * BM) >> 12;
;         f32x4 gv[2][2];
; #pragma unroll
;         for (int bj = 0; bj < 2; ++bj)
; #pragma unroll
;             for (int n = 0; n < 2; ++n) gv[bj][n] = *(const f32x4*)(gate + (size_t)b * gate_ld + col0 + bj * HALF + n * 4);
;         f32x4 xv[2][2][2];
;         load_x(xv[0], (size_t)row0 * 1024 + col0);
; #pragma unroll
;         for (int g = 0; g < 8; ++g) { const int ai = g >> 2, m = g & 3; const size_t off = (size_t)(row0 + ai * HALF + m * 16) * 1024 + col0;
;             if (g + 1 < 8) { const int ai2 = (g + 1) >> 2, m2 = (g + 1) & 3; load_x(xv[(g + 1) & 1], (size_t)(row0 + ai2 * HALF + m2 * 16) * 1024 + col0); }
;             float rs_ = 1.0f; if constexpr (ROWSCALE) rs_ = tab[((u.pm == pm0 ? 0 : 256) + ai * HALF + wr * 64 + m * 16 + fr) * 2 + 1];
; #pragma unroll
;             for (int bj = 0; bj < 2; ++bj) { const f32x4 v0 = xv[g & 1][bj][0] + gv[bj][0] * (acc[ai][bj][m][0] * rs_), v1 = xv[g & 1][bj][1] + gv[bj][1] * (acc[ai][bj][m][1] * rs_);
;                 u32x4 w; w.x = cvt_pk_bf16(v0[0], v0[1]); w.y = cvt_pk_bf16(v0[2], v0[3]); w.z = cvt_pk_bf16(v1[0], v1[1]); w.w = cvt_pk_bf16(v1[2], v1[3]);
;                 *(u32x4*)(out + off + bj * HALF) = w; } }
.LBB0_417:
	v_lshl_or_b32 v221, s5, 8, v203
	s_ashr_i32 s3, s4, 4
	s_mul_hi_i32 s5, s3, 0x6000
	s_mulk_i32 s3, 0x6000
	s_add_u32 s12, s64, s3
	s_addc_u32 s13, s65, s5
	v_lshlrev_b32_e32 v223, 2, v221
	global_load_dwordx4 v[60:63], v223, s[12:13]
	global_load_dwordx4 v[56:59], v223, s[12:13] offset:16
	global_load_dwordx4 v[52:55], v223, s[12:13] offset:512
	global_load_dwordx4 v[48:51], v223, s[12:13] offset:528
	v_lshlrev_b32_e32 v213, 11, v198
	v_lshl_add_u32 v213, v221, 1, v213
	s_lshl_b32 s3, s4, 19
	s_add_u32 s98, s38, s3
	s_addc_u32 s99, s39, 0
	s_mov_b64 s[100:101], s[98:99]
	v_readlane_b32 s3, v255, 49
	s_nop 0
	s_cmp_eq_u32 s4, s3
	s_cselect_b32 s4, 0, 0x100
	v_add_u32_e32 v80, s4, v198
	s_add_i32 s5, 0, 0x22800
	v_lshl_add_u32 v80, v80, 3, s5
	s_mov_b32 s3, 0x40000
	s_mov_b64 s[12:13], 0x40000
	s_mov_b32 s78, s1
	global_load_dwordx4 v[176:179], v213, s[98:99]
	global_load_dwordx4 v[180:183], v213, s[98:99] offset:256
	s_add_u32 s98, s98, 0x8000
	s_addc_u32 s99, s99, 0
	global_load_dwordx4 v[184:187], v213, s[98:99]
	global_load_dwordx4 v[188:191], v213, s[98:99] offset:256
	s_add_u32 s98, s98, 0x8000
	s_addc_u32 s99, s99, 0
	global_load_dwordx4 v[192:195], v213, s[98:99]
	global_load_dwordx4 v[224:227], v213, s[98:99] offset:256
	s_add_u32 s98, s98, 0x8000
	s_addc_u32 s99, s99, 0
	global_load_dwordx4 v[232:235], v213, s[98:99]
	global_load_dwordx4 v[236:239], v213, s[98:99] offset:256
	s_add_u32 s98, s98, 0x28000
	s_addc_u32 s99, s99, 0
	global_load_dwordx4 v[240:243], v213, s[98:99]
	global_load_dwordx4 v[244:247], v213, s[98:99] offset:256
	s_add_u32 s98, s98, 0x8000
	s_addc_u32 s99, s99, 0
	ds_read_b32 v212, v80 offset:4
	ds_read_b32 v220, v80 offset:132
	ds_read_b32 v222, v80 offset:260
	ds_read_b32 v228, v80 offset:388
	ds_read_b32 v230, v80 offset:1028
	ds_read_b32 v248, v80 offset:1156
	ds_read_b32 v250, v80 offset:1284
	ds_read_b32 v82, v80 offset:1412
	s_waitcnt lgkmcnt(0)
	s_waitcnt vmcnt(8)
	v_pk_mul_f32 v[144:145], v[144:145], v[212:213] op_sel_hi:[1,0]
	v_pk_mul_f32 v[146:147], v[146:147], v[212:213] op_sel_hi:[1,0]
	v_pk_mul_f32 v[140:141], v[140:141], v[212:213] op_sel_hi:[1,0]
	v_pk_mul_f32 v[142:143], v[142:143], v[212:213] op_sel_hi:[1,0]
	v_lshlrev_b32_e32 v160, 16, v176
	v_and_b32_e32 v161, 0xffff0000, v176
	v_lshlrev_b32_e32 v174, 16, v177
	v_and_b32_e32 v175, 0xffff0000, v177
	v_lshlrev_b32_e32 v196, 16, v178
	v_and_b32_e32 v197, 0xffff0000, v178
	v_lshlrev_b32_e32 v210, 16, v179
	v_and_b32_e32 v211, 0xffff0000, v179
	v_pk_fma_f32 v[144:145], v[60:61], v[144:145], v[160:161]
	v_pk_fma_f32 v[146:147], v[62:63], v[146:147], v[174:175]
	v_pk_fma_f32 v[140:141], v[56:57], v[140:141], v[196:197]
	v_pk_fma_f32 v[142:143], v[58:59], v[142:143], v[210:211]
	v_cvt_pk_bf16_f32 v176, v144, v145
	v_cvt_pk_bf16_f32 v177, v146, v147
	v_cvt_pk_bf16_f32 v178, v140, v141
	v_cvt_pk_bf16_f32 v179, v142, v143
	global_store_dwordx4 v213, v[176:179], s[100:101]
	v_pk_mul_f32 v[136:137], v[136:137], v[212:213] op_sel_hi:[1,0]
	v_pk_mul_f32 v[138:139], v[138:139], v[212:213] op_sel_hi:[1,0]
	v_pk_mul_f32 v[132:133], v[132:133], v[212:213] op_sel_hi:[1,0]
	v_pk_mul_f32 v[134:135], v[134:135], v[212:213] op_sel_hi:[1,0]
	v_lshlrev_b32_e32 v160, 16, v180
	v_and_b32_e32 v161, 0xffff0000, v180
	v_lshlrev_b32_e32 v174, 16, v181
	v_and_b32_e32 v175, 0xffff0000, v181
	v_lshlrev_b32_e32 v196, 16, v182
	v_and_b32_e32 v197, 0xffff0000, v182
	v_lshlrev_b32_e32 v210, 16, v183
	v_and_b32_e32 v211, 0xffff0000, v183
	v_pk_fma_f32 v[136:137], v[52:53], v[136:137], v[160:161]
	v_pk_fma_f32 v[138:139], v[54:55], v[138:139], v[174:175]
	v_pk_fma_f32 v[132:133], v[48:49], v[132:133], v[196:197]
	v_pk_fma_f32 v[134:135], v[50:51], v[134:135], v[210:211]
	v_cvt_pk_bf16_f32 v180, v136, v137
	v_cvt_pk_bf16_f32 v181, v138, v139
	v_cvt_pk_bf16_f32 v182, v132, v133
	v_cvt_pk_bf16_f32 v183, v134, v135
	global_store_dwordx4 v213, v[180:183], s[100:101] offset:256
	s_add_u32 s100, s100, 0x8000
	s_addc_u32 s101, s101, 0
	global_load_dwordx4 v[176:179], v213, s[98:99]
	global_load_dwordx4 v[180:183], v213, s[98:99] offset:256
	s_add_u32 s98, s98, 0x8000
	s_addc_u32 s99, s99, 0
	s_waitcnt vmcnt(10)
	v_pk_mul_f32 v[128:129], v[128:129], v[220:221] op_sel_hi:[1,0]
	v_pk_mul_f32 v[130:131], v[130:131], v[220:221] op_sel_hi:[1,0]
	v_pk_mul_f32 v[124:125], v[124:125], v[220:221] op_sel_hi:[1,0]
	v_pk_mul_f32 v[126:127], v[126:127], v[220:221] op_sel_hi:[1,0]
	v_lshlrev_b32_e32 v160, 16, v184
	v_and_b32_e32 v161, 0xffff0000, v184
	v_lshlrev_b32_e32 v174, 16, v185
	v_and_b32_e32 v175, 0xffff0000, v185
	v_lshlrev_b32_e32 v196, 16, v186
	v_and_b32_e32 v197, 0xffff0000, v186
	v_lshlrev_b32_e32 v210, 16, v187
	v_and_b32_e32 v211, 0xffff0000, v187
	v_pk_fma_f32 v[128:129], v[60:61], v[128:129], v[160:161]
	v_pk_fma_f32 v[130:131], v[62:63], v[130:131], v[174:175]
	v_pk_fma_f32 v[124:125], v[56:57], v[124:125], v[196:197]
	v_pk_fma_f32 v[126:127], v[58:59], v[126:127], v[210:211]
	v_cvt_pk_bf16_f32 v184, v128, v129
	v_cvt_pk_bf16_f32 v185, v130, v131
	v_cvt_pk_bf16_f32 v186, v124, v125
	v_cvt_pk_bf16_f32 v187, v126, v127
	global_store_dwordx4 v213, v[184:187], s[100:101]
	v_pk_mul_f32 v[120:121], v[120:121], v[220:221] op_sel_hi:[1,0]
	v_pk_mul_f32 v[122:123], v[122:123], v[220:221] op_sel_hi:[1,0]
	v_pk_mul_f32 v[116:117], v[116:117], v[220:221] op_sel_hi:[1,0]
	v_pk_mul_f32 v[118:119], v[118:119], v[220:221] op_sel_hi:[1,0]
	v_lshlrev_b32_e32 v160, 16, v188
	v_and_b32_e32 v161, 0xffff0000, v188
	v_lshlrev_b32_e32 v174, 16, v189
	v_and_b32_e32 v175, 0xffff0000, v189
	v_lshlrev_b32_e32 v196, 16, v190
	v_and_b32_e32 v197, 0xffff0000, v190
	v_lshlrev_b32_e32 v210, 16, v191
	v_and_b32_e32 v211, 0xffff0000, v191
	v_pk_fma_f32 v[120:121], v[52:53], v[120:121], v[160:161]
	v_pk_fma_f32 v[122:123], v[54:55], v[122:123], v[174:175]
	v_pk_fma_f32 v[116:117], v[48:49], v[116:117], v[196:197]
	v_pk_fma_f32 v[118:119], v[50:51], v[118:119], v[210:211]
	v_cvt_pk_bf16_f32 v188, v120, v121
	v_cvt_pk_bf16_f32 v189, v122, v123
	v_cvt_pk_bf16_f32 v190, v116, v117
	v_cvt_pk_bf16_f32 v191, v118, v119
	global_store_dwordx4 v213, v[188:191], s[100:101] offset:256
	s_add_u32 s100, s100, 0x8000
	s_addc_u32 s101, s101, 0
	global_load_dwordx4 v[184:187], v213, s[98:99]
	global_load_dwordx4 v[188:191], v213, s[98:99] offset:256
	s_add_u32 s98, s98, 0x8000
	s_addc_u32 s99, s99, 0
	s_waitcnt vmcnt(12)
; __device__ __forceinline__ unsigned cvt_pk_bf16(float lo, float hi) { f32x2_cv v = {lo, hi}; bf16x2_cv b = __builtin_convertvector(v, bf16x2_cv); return __builtin_bit_cast(unsigned, b); }
;     __device__ __forceinline__ void operator()(const f32x4 (&acc)[2][2][4][2], const Unit& u, int wr, int wc, int fr, int fq) const {
;     ...
;         for (int g = 0; g < 8; ++g) { const int ai = g >> 2, m = g & 3; const size_t off = (size_t)(row0 + ai * HALF + m * 16) * 1024 + col0;
;             if (g + 1 < 8) { const int ai2 = (g + 1) >> 2, m2 = (g + 1) & 3; load_x(xv[(g + 1) & 1], (size_t)(row0 + ai2 * HALF + m2 * 16) * 1024 + col0); }
;             float rs_ = 1.0f; if constexpr (ROWSCALE) rs_ = tab[((u.pm == pm0 ? 0 : 256) + ai * HALF + wr * 64 + m * 16 + fr) * 2 + 1];
; #pragma unroll
;             for (int bj = 0; bj < 2; ++bj) { const f32x4 v0 = xv[g & 1][bj][0] + gv[bj][0] * (acc[ai][bj][m][0] * rs_), v1 = xv[g & 1][bj][1] + gv[bj][1] * (acc[ai][bj][m][1] * rs_);
;                 u32x4 w; w.x = cvt_pk_bf16(v0[0], v0[1]); w.y = cvt_pk_bf16(v0[2], v0[3]); w.z = cvt_pk_bf16(v1[0], v1[1]); w.w = cvt_pk_bf16(v1[2], v1[3]);
;                 *(u32x4*)(out + off + bj * HALF) = w; } }
	v_pk_mul_f32 v[112:113], v[112:113], v[222:223] op_sel_hi:[1,0]
	v_pk_mul_f32 v[114:115], v[114:115], v[222:223] op_sel_hi:[1,0]
	v_pk_mul_f32 v[108:109], v[108:109], v[222:223] op_sel_hi:[1,0]
	v_pk_mul_f32 v[110:111], v[110:111], v[222:223] op_sel_hi:[1,0]
	v_lshlrev_b32_e32 v160, 16, v192
	v_and_b32_e32 v161, 0xffff0000, v192
	v_lshlrev_b32_e32 v174, 16, v193
	v_and_b32_e32 v175, 0xffff0000, v193
	v_lshlrev_b32_e32 v196, 16, v194
	v_and_b32_e32 v197, 0xffff0000, v194
	v_lshlrev_b32_e32 v210, 16, v195
	v_and_b32_e32 v211, 0xffff0000, v195
	v_pk_fma_f32 v[112:113], v[60:61], v[112:113], v[160:161]
	v_pk_fma_f32 v[114:115], v[62:63], v[114:115], v[174:175]
	v_pk_fma_f32 v[108:109], v[56:57], v[108:109], v[196:197]
	v_pk_fma_f32 v[110:111], v[58:59], v[110:111], v[210:211]
	v_cvt_pk_bf16_f32 v192, v112, v113
	v_cvt_pk_bf16_f32 v193, v114, v115
	v_cvt_pk_bf16_f32 v194, v108, v109
	v_cvt_pk_bf16_f32 v195, v110, v111
	global_store_dwordx4 v213, v[192:195], s[100:101]
	v_pk_mul_f32 v[104:105], v[104:105], v[222:223] op_sel_hi:[1,0]
	v_pk_mul_f32 v[106:107], v[106:107], v[222:223] op_sel_hi:[1,0]
	v_pk_mul_f32 v[100:101], v[100:101], v[222:223] op_sel_hi:[1,0]
	v_pk_mul_f32 v[102:103], v[102:103], v[222:223] op_sel_hi:[1,0]
	v_lshlrev_b32_e32 v160, 16, v224
	v_and_b32_e32 v161, 0xffff0000, v224
	v_lshlrev_b32_e32 v174, 16, v225
	v_and_b32_e32 v175, 0xffff0000, v225
	v_lshlrev_b32_e32 v196, 16, v226
	v_and_b32_e32 v197, 0xffff0000, v226
	v_lshlrev_b32_e32 v210, 16, v227
	v_and_b32_e32 v211, 0xffff0000, v227
	v_pk_fma_f32 v[104:105], v[52:53], v[104:105], v[160:161]
	v_pk_fma_f32 v[106:107], v[54:55], v[106:107], v[174:175]
	v_pk_fma_f32 v[100:101], v[48:49], v[100:101], v[196:197]
	v_pk_fma_f32 v[102:103], v[50:51], v[102:103], v[210:211]
	v_cvt_pk_bf16_f32 v224, v104, v105
	v_cvt_pk_bf16_f32 v225, v106, v107
	v_cvt_pk_bf16_f32 v226, v100, v101
	v_cvt_pk_bf16_f32 v227, v102, v103
	global_store_dwordx4 v213, v[224:227], s[100:101] offset:256
	s_add_u32 s100, s100, 0x8000
	s_addc_u32 s101, s101, 0
	global_load_dwordx4 v[192:195], v213, s[98:99]
	global_load_dwordx4 v[224:227], v213, s[98:99] offset:256
	s_add_u32 s98, s98, 0x8000
	s_addc_u32 s99, s99, 0
	s_waitcnt vmcnt(14)
	v_pk_mul_f32 v[96:97], v[96:97], v[228:229] op_sel_hi:[1,0]
	v_pk_mul_f32 v[98:99], v[98:99], v[228:229] op_sel_hi:[1,0]
	v_pk_mul_f32 v[92:93], v[92:93], v[228:229] op_sel_hi:[1,0]
	v_pk_mul_f32 v[94:95], v[94:95], v[228:229] op_sel_hi:[1,0]
	v_lshlrev_b32_e32 v160, 16, v232
	v_and_b32_e32 v161, 0xffff0000, v232
	v_lshlrev_b32_e32 v174, 16, v233
	v_and_b32_e32 v175, 0xffff0000, v233
	v_lshlrev_b32_e32 v196, 16, v234
	v_and_b32_e32 v197, 0xffff0000, v234
	v_lshlrev_b32_e32 v210, 16, v235
	v_and_b32_e32 v211, 0xffff0000, v235
	v_pk_fma_f32 v[96:97], v[60:61], v[96:97], v[160:161]
	v_pk_fma_f32 v[98:99], v[62:63], v[98:99], v[174:175]
	v_pk_fma_f32 v[92:93], v[56:57], v[92:93], v[196:197]
	v_pk_fma_f32 v[94:95], v[58:59], v[94:95], v[210:211]
	v_cvt_pk_bf16_f32 v232, v96, v97
	v_cvt_pk_bf16_f32 v233, v98, v99
	v_cvt_pk_bf16_f32 v234, v92, v93
	v_cvt_pk_bf16_f32 v235, v94, v95
	global_store_dwordx4 v213, v[232:235], s[100:101]
	v_pk_mul_f32 v[88:89], v[88:89], v[228:229] op_sel_hi:[1,0]
	v_pk_mul_f32 v[90:91], v[90:91], v[228:229] op_sel_hi:[1,0]
	v_pk_mul_f32 v[84:85], v[84:85], v[228:229] op_sel_hi:[1,0]
	v_pk_mul_f32 v[86:87], v[86:87], v[228:229] op_sel_hi:[1,0]
	v_lshlrev_b32_e32 v160, 16, v236
	v_and_b32_e32 v161, 0xffff0000, v236
	v_lshlrev_b32_e32 v174, 16, v237
	v_and_b32_e32 v175, 0xffff0000, v237
	v_lshlrev_b32_e32 v196, 16, v238
	v_and_b32_e32 v197, 0xffff0000, v238
	v_lshlrev_b32_e32 v210, 16, v239
	v_and_b32_e32 v211, 0xffff0000, v239
	v_pk_fma_f32 v[88:89], v[52:53], v[88:89], v[160:161]
	v_pk_fma_f32 v[90:91], v[54:55], v[90:91], v[174:175]
	v_pk_fma_f32 v[84:85], v[48:49], v[84:85], v[196:197]
	v_pk_fma_f32 v[86:87], v[50:51], v[86:87], v[210:211]
	v_cvt_pk_bf16_f32 v236, v88, v89
	v_cvt_pk_bf16_f32 v237, v90, v91
	v_cvt_pk_bf16_f32 v238, v84, v85
	v_cvt_pk_bf16_f32 v239, v86, v87
	global_store_dwordx4 v213, v[236:239], s[100:101] offset:256
	s_add_u32 s100, s100, 0x28000
	s_addc_u32 s101, s101, 0
	s_waitcnt vmcnt(14)
	v_pk_mul_f32 v[76:77], v[76:77], v[230:231] op_sel_hi:[1,0]
	v_pk_mul_f32 v[78:79], v[78:79], v[230:231] op_sel_hi:[1,0]
	v_pk_mul_f32 v[72:73], v[72:73], v[230:231] op_sel_hi:[1,0]
	v_pk_mul_f32 v[74:75], v[74:75], v[230:231] op_sel_hi:[1,0]
	v_lshlrev_b32_e32 v160, 16, v240
	v_and_b32_e32 v161, 0xffff0000, v240
	v_lshlrev_b32_e32 v174, 16, v241
	v_and_b32_e32 v175, 0xffff0000, v241
	v_lshlrev_b32_e32 v196, 16, v242
	v_and_b32_e32 v197, 0xffff0000, v242
	v_lshlrev_b32_e32 v210, 16, v243
	v_and_b32_e32 v211, 0xffff0000, v243
	v_pk_fma_f32 v[76:77], v[60:61], v[76:77], v[160:161]
	v_pk_fma_f32 v[78:79], v[62:63], v[78:79], v[174:175]
	v_pk_fma_f32 v[72:73], v[56:57], v[72:73], v[196:197]
	v_pk_fma_f32 v[74:75], v[58:59], v[74:75], v[210:211]
	v_cvt_pk_bf16_f32 v240, v76, v77
	v_cvt_pk_bf16_f32 v241, v78, v79
	v_cvt_pk_bf16_f32 v242, v72, v73
	v_cvt_pk_bf16_f32 v243, v74, v75
	global_store_dwordx4 v213, v[240:243], s[100:101]
	v_pk_mul_f32 v[68:69], v[68:69], v[230:231] op_sel_hi:[1,0]
	v_pk_mul_f32 v[70:71], v[70:71], v[230:231] op_sel_hi:[1,0]
	v_pk_mul_f32 v[64:65], v[64:65], v[230:231] op_sel_hi:[1,0]
	v_pk_mul_f32 v[66:67], v[66:67], v[230:231] op_sel_hi:[1,0]
	v_lshlrev_b32_e32 v160, 16, v244
	v_and_b32_e32 v161, 0xffff0000, v244
	v_lshlrev_b32_e32 v174, 16, v245
	v_and_b32_e32 v175, 0xffff0000, v245
	v_lshlrev_b32_e32 v196, 16, v246
	v_and_b32_e32 v197, 0xffff0000, v246
	v_lshlrev_b32_e32 v210, 16, v247
	v_and_b32_e32 v211, 0xffff0000, v247
	v_pk_fma_f32 v[68:69], v[52:53], v[68:69], v[160:161]
	v_pk_fma_f32 v[70:71], v[54:55], v[70:71], v[174:175]
	v_pk_fma_f32 v[64:65], v[48:49], v[64:65], v[196:197]
	v_pk_fma_f32 v[66:67], v[50:51], v[66:67], v[210:211]
	v_cvt_pk_bf16_f32 v244, v68, v69
	v_cvt_pk_bf16_f32 v245, v70, v71
	v_cvt_pk_bf16_f32 v246, v64, v65
	v_cvt_pk_bf16_f32 v247, v66, v67
	global_store_dwordx4 v213, v[244:247], s[100:101] offset:256
	s_add_u32 s100, s100, 0x8000
	s_addc_u32 s101, s101, 0
	s_waitcnt vmcnt(12)
; __device__ __forceinline__ unsigned cvt_pk_bf16(float lo, float hi) { f32x2_cv v = {lo, hi}; bf16x2_cv b = __builtin_convertvector(v, bf16x2_cv); return __builtin_bit_cast(unsigned, b); }
;     __device__ __forceinline__ void operator()(const f32x4 (&acc)[2][2][4][2], const Unit& u, int wr, int wc, int fr, int fq) const {
;     ...
;         for (int g = 0; g < 8; ++g) { const int ai = g >> 2, m = g & 3; const size_t off = (size_t)(row0 + ai * HALF + m * 16) * 1024 + col0;
;             if (g + 1 < 8) { const int ai2 = (g + 1) >> 2, m2 = (g + 1) & 3; load_x(xv[(g + 1) & 1], (size_t)(row0 + ai2 * HALF + m2 * 16) * 1024 + col0); }
;             float rs_ = 1.0f; if constexpr (ROWSCALE) rs_ = tab[((u.pm == pm0 ? 0 : 256) + ai * HALF + wr * 64 + m * 16 + fr) * 2 + 1];
; #pragma unroll
;             for (int bj = 0; bj < 2; ++bj) { const f32x4 v0 = xv[g & 1][bj][0] + gv[bj][0] * (acc[ai][bj][m][0] * rs_), v1 = xv[g & 1][bj][1] + gv[bj][1] * (acc[ai][bj][m][1] * rs_);
;                 u32x4 w; w.x = cvt_pk_bf16(v0[0], v0[1]); w.y = cvt_pk_bf16(v0[2], v0[3]); w.z = cvt_pk_bf16(v1[0], v1[1]); w.w = cvt_pk_bf16(v1[2], v1[3]);
;                 *(u32x4*)(out + off + bj * HALF) = w; } }
	v_pk_mul_f32 v[44:45], v[44:45], v[248:249] op_sel_hi:[1,0]
	v_pk_mul_f32 v[46:47], v[46:47], v[248:249] op_sel_hi:[1,0]
	v_pk_mul_f32 v[40:41], v[40:41], v[248:249] op_sel_hi:[1,0]
	v_pk_mul_f32 v[42:43], v[42:43], v[248:249] op_sel_hi:[1,0]
	v_lshlrev_b32_e32 v160, 16, v176
	v_and_b32_e32 v161, 0xffff0000, v176
	v_lshlrev_b32_e32 v174, 16, v177
	v_and_b32_e32 v175, 0xffff0000, v177
	v_lshlrev_b32_e32 v196, 16, v178
	v_and_b32_e32 v197, 0xffff0000, v178
	v_lshlrev_b32_e32 v210, 16, v179
	v_and_b32_e32 v211, 0xffff0000, v179
	v_pk_fma_f32 v[44:45], v[60:61], v[44:45], v[160:161]
	v_pk_fma_f32 v[46:47], v[62:63], v[46:47], v[174:175]
	v_pk_fma_f32 v[40:41], v[56:57], v[40:41], v[196:197]
	v_pk_fma_f32 v[42:43], v[58:59], v[42:43], v[210:211]
	v_cvt_pk_bf16_f32 v176, v44, v45
	v_cvt_pk_bf16_f32 v177, v46, v47
	v_cvt_pk_bf16_f32 v178, v40, v41
	v_cvt_pk_bf16_f32 v179, v42, v43
	global_store_dwordx4 v213, v[176:179], s[100:101]
	v_pk_mul_f32 v[36:37], v[36:37], v[248:249] op_sel_hi:[1,0]
	v_pk_mul_f32 v[38:39], v[38:39], v[248:249] op_sel_hi:[1,0]
	v_pk_mul_f32 v[32:33], v[32:33], v[248:249] op_sel_hi:[1,0]
	v_pk_mul_f32 v[34:35], v[34:35], v[248:249] op_sel_hi:[1,0]
	v_lshlrev_b32_e32 v160, 16, v180
	v_and_b32_e32 v161, 0xffff0000, v180
	v_lshlrev_b32_e32 v174, 16, v181
	v_and_b32_e32 v175, 0xffff0000, v181
	v_lshlrev_b32_e32 v196, 16, v182
	v_and_b32_e32 v197, 0xffff0000, v182
	v_lshlrev_b32_e32 v210, 16, v183
	v_and_b32_e32 v211, 0xffff0000, v183
	v_pk_fma_f32 v[36:37], v[52:53], v[36:37], v[160:161]
	v_pk_fma_f32 v[38:39], v[54:55], v[38:39], v[174:175]
	v_pk_fma_f32 v[32:33], v[48:49], v[32:33], v[196:197]
	v_pk_fma_f32 v[34:35], v[50:51], v[34:35], v[210:211]
	v_cvt_pk_bf16_f32 v180, v36, v37
	v_cvt_pk_bf16_f32 v181, v38, v39
	v_cvt_pk_bf16_f32 v182, v32, v33
	v_cvt_pk_bf16_f32 v183, v34, v35
	global_store_dwordx4 v213, v[180:183], s[100:101] offset:256
	s_add_u32 s100, s100, 0x8000
	s_addc_u32 s101, s101, 0
	s_waitcnt vmcnt(10)
	v_pk_mul_f32 v[28:29], v[28:29], v[250:251] op_sel_hi:[1,0]
	v_pk_mul_f32 v[30:31], v[30:31], v[250:251] op_sel_hi:[1,0]
	v_pk_mul_f32 v[24:25], v[24:25], v[250:251] op_sel_hi:[1,0]
	v_pk_mul_f32 v[26:27], v[26:27], v[250:251] op_sel_hi:[1,0]
	v_lshlrev_b32_e32 v160, 16, v184
	v_and_b32_e32 v161, 0xffff0000, v184
	v_lshlrev_b32_e32 v174, 16, v185
	v_and_b32_e32 v175, 0xffff0000, v185
	v_lshlrev_b32_e32 v196, 16, v186
	v_and_b32_e32 v197, 0xffff0000, v186
	v_lshlrev_b32_e32 v210, 16, v187
	v_and_b32_e32 v211, 0xffff0000, v187
	v_pk_fma_f32 v[28:29], v[60:61], v[28:29], v[160:161]
	v_pk_fma_f32 v[30:31], v[62:63], v[30:31], v[174:175]
	v_pk_fma_f32 v[24:25], v[56:57], v[24:25], v[196:197]
	v_pk_fma_f32 v[26:27], v[58:59], v[26:27], v[210:211]
	v_cvt_pk_bf16_f32 v184, v28, v29
	v_cvt_pk_bf16_f32 v185, v30, v31
	v_cvt_pk_bf16_f32 v186, v24, v25
	v_cvt_pk_bf16_f32 v187, v26, v27
	global_store_dwordx4 v213, v[184:187], s[100:101]
	v_pk_mul_f32 v[20:21], v[20:21], v[250:251] op_sel_hi:[1,0]
	v_pk_mul_f32 v[22:23], v[22:23], v[250:251] op_sel_hi:[1,0]
	v_pk_mul_f32 v[16:17], v[16:17], v[250:251] op_sel_hi:[1,0]
	v_pk_mul_f32 v[18:19], v[18:19], v[250:251] op_sel_hi:[1,0]
	v_lshlrev_b32_e32 v160, 16, v188
	v_and_b32_e32 v161, 0xffff0000, v188
	v_lshlrev_b32_e32 v174, 16, v189
	v_and_b32_e32 v175, 0xffff0000, v189
	v_lshlrev_b32_e32 v196, 16, v190
	v_and_b32_e32 v197, 0xffff0000, v190
	v_lshlrev_b32_e32 v210, 16, v191
	v_and_b32_e32 v211, 0xffff0000, v191
	v_pk_fma_f32 v[20:21], v[52:53], v[20:21], v[160:161]
	v_pk_fma_f32 v[22:23], v[54:55], v[22:23], v[174:175]
	v_pk_fma_f32 v[16:17], v[48:49], v[16:17], v[196:197]
	v_pk_fma_f32 v[18:19], v[50:51], v[18:19], v[210:211]
	v_cvt_pk_bf16_f32 v188, v20, v21
	v_cvt_pk_bf16_f32 v189, v22, v23
	v_cvt_pk_bf16_f32 v190, v16, v17
	v_cvt_pk_bf16_f32 v191, v18, v19
	global_store_dwordx4 v213, v[188:191], s[100:101] offset:256
	s_add_u32 s100, s100, 0x8000
	s_addc_u32 s101, s101, 0
	s_waitcnt vmcnt(8)
	v_pk_mul_f32 v[12:13], v[12:13], v[82:83] op_sel_hi:[1,0]
	v_pk_mul_f32 v[14:15], v[14:15], v[82:83] op_sel_hi:[1,0]
	v_pk_mul_f32 v[8:9], v[8:9], v[82:83] op_sel_hi:[1,0]
	v_pk_mul_f32 v[10:11], v[10:11], v[82:83] op_sel_hi:[1,0]
	v_lshlrev_b32_e32 v160, 16, v192
	v_and_b32_e32 v161, 0xffff0000, v192
	v_lshlrev_b32_e32 v174, 16, v193
	v_and_b32_e32 v175, 0xffff0000, v193
	v_lshlrev_b32_e32 v196, 16, v194
	v_and_b32_e32 v197, 0xffff0000, v194
	v_lshlrev_b32_e32 v210, 16, v195
	v_and_b32_e32 v211, 0xffff0000, v195
	v_pk_fma_f32 v[12:13], v[60:61], v[12:13], v[160:161]
	v_pk_fma_f32 v[14:15], v[62:63], v[14:15], v[174:175]
	v_pk_fma_f32 v[8:9], v[56:57], v[8:9], v[196:197]
	v_pk_fma_f32 v[10:11], v[58:59], v[10:11], v[210:211]
	v_cvt_pk_bf16_f32 v192, v12, v13
	v_cvt_pk_bf16_f32 v193, v14, v15
	v_cvt_pk_bf16_f32 v194, v8, v9
	v_cvt_pk_bf16_f32 v195, v10, v11
	global_store_dwordx4 v213, v[192:195], s[100:101]
	v_pk_mul_f32 v[4:5], v[4:5], v[82:83] op_sel_hi:[1,0]
	v_pk_mul_f32 v[6:7], v[6:7], v[82:83] op_sel_hi:[1,0]
	v_pk_mul_f32 v[0:1], v[0:1], v[82:83] op_sel_hi:[1,0]
	v_pk_mul_f32 v[2:3], v[2:3], v[82:83] op_sel_hi:[1,0]
	v_lshlrev_b32_e32 v160, 16, v224
	v_and_b32_e32 v161, 0xffff0000, v224
	v_lshlrev_b32_e32 v174, 16, v225
	v_and_b32_e32 v175, 0xffff0000, v225
	v_lshlrev_b32_e32 v196, 16, v226
	v_and_b32_e32 v197, 0xffff0000, v226
	v_lshlrev_b32_e32 v210, 16, v227
	v_and_b32_e32 v211, 0xffff0000, v227
	v_pk_fma_f32 v[4:5], v[52:53], v[4:5], v[160:161]
	v_pk_fma_f32 v[6:7], v[54:55], v[6:7], v[174:175]
	v_pk_fma_f32 v[0:1], v[48:49], v[0:1], v[196:197]
	v_pk_fma_f32 v[2:3], v[50:51], v[2:3], v[210:211]
	v_cvt_pk_bf16_f32 v224, v4, v5
	v_cvt_pk_bf16_f32 v225, v6, v7
	v_cvt_pk_bf16_f32 v226, v0, v1
	v_cvt_pk_bf16_f32 v227, v2, v3
	global_store_dwordx4 v213, v[224:227], s[100:101] offset:256
	s_add_u32 s100, s100, 0x8000
	s_addc_u32 s101, s101, 0
	s_mov_b64 s[4:5], -1
	s_andn2_b64 vcc, exec, s[36:37]
	s_cbranch_vccnz .LBB0_404
	s_andn2_b64 vcc, exec, s[42:43]
	s_cbranch_vccnz .LBB0_403
	s_barrier
	s_branch .LBB0_403
